# comb12 + first-unit rstd loads of the two FFN-in phases issued ahead of the prologue's second tile batch (no vmcnt(0) drain of in-flight tile loads at the preheader)
# speedup vs baseline: 1.0048x; 1.0048x over previous
; #define PG8_STAGE(bufoff, gbase, voff) do { _Pragma("unroll") for (int _i = 0; _i < 2; ++_i) \
;         __builtin_amdgcn_global_load_lds((const unsigned*)((const char*)(gbase) + (voff)[_i]), (LAS unsigned*)(lds + (bufoff) + ldsw + _i * 8192), 16, 0, 0); } while (0)
; #define PG8_WAIT_V(n) asm volatile("s_waitcnt vmcnt(" #n ")" ::: "memory")
; #define PG8_BAR __builtin_amdgcn_s_barrier()
; __device__ __forceinline__ void load_rstd(const float* part, int row0, int fq, float (&rs)[2][4]) {
; #pragma unroll
;     for (int ai = 0; ai < 2; ++ai)
; #pragma unroll
;         for (int m = 0; m < 4; ++m) { const float* p = part + (size_t)(row0 + ai * HALF + m * 16) * NPART + fq * 8;
;             const f32x4 a = *(const f32x4*)p, b = *(const f32x4*)(p + 4); float s = ((a[0] + a[1]) + (a[2] + a[3])) + ((b[0] + b[1]) + (b[2] + b[3]));
;             s += __shfl_xor(s, 16); s += __shfl_xor(s, 32); rs[ai][m] = rsqrtf(s * (1.0f / D) + RMS_EPS); }
; template <class Epi, class Sched, bool ALIGN_EPI>
; __device__ __forceinline__ void gemm_phase(LAS unsigned char* lds, const Gemm g, const Sched& S, const Epi& E) {
;     ...
;     PG8_STAGE(PG8_SB(0, 0), cB, voffB); PG8_STAGE(PG8_SB(0, 1), cB + hB, voffB); PG8_STAGE(PG8_SA(0, 0), cA, voffA); PG8_STAGE(PG8_SA(0, 1), cA + hA, voffA);
;     if (wr == 1) PG8_BAR;
;     PG8_WAIT_V(2); PG8_BAR;
;     PG8_STAGE(PG8_SB(1, 0), cB + kstep, voffB); PG8_STAGE(PG8_SA(1, 0), cA + kstep, voffA); PG8_STAGE(PG8_SB(1, 1), cB + hB + kstep, voffB);
;     PG8_WAIT_V(6); PG8_BAR;
.LBB0_255:
	s_lshl_b32 s19, s36, 5
	s_mov_b64 s[36:37], 0x80
	s_add_i32 m0, s70, 0x18000
	v_lshl_add_u64 v[6:7], v[6:7], 0, s[36:37]
	s_lshl_b32 s18, s3, 13
	s_and_b32 s19, s19, 0x60
	s_waitcnt vmcnt(2)
	s_barrier
	v_lshrrev_b32_e32 v216, 1, v220
	s_lshl_b32 s96, s11, 8
	s_lshl_b32 s97, s95, 5
	s_add_i32 s96, s96, s97
	v_add_u32_e32 v216, s96, v216
	v_and_b32_e32 v217, 1, v220
	v_lshlrev_b32_e32 v217, 6, v217
	v_lshl_add_u32 v216, v216, 7, v217
	s_add_u32 s96, s14, 0xc300000
	s_addc_u32 s97, s15, 0
	global_load_dwordx4 v[200:203], v216, s[96:97]
	global_load_dwordx4 v[204:207], v216, s[96:97] offset:16
	global_load_dwordx4 v[208:211], v216, s[96:97] offset:32
	global_load_dwordx4 v[212:215], v216, s[96:97] offset:48
	global_load_lds_dwordx4 v[6:7], off
	v_lshl_add_u64 v[4:5], v[4:5], 0, s[36:37]
	s_add_i32 m0, s70, 0x1a000
	s_add_i32 s78, s70, 0x8000
	s_add_i32 s79, s70, 0xa000
	global_load_lds_dwordx4 v[4:5], off
	v_lshl_add_u64 v[0:1], v[0:1], 0, s[36:37]
	s_mov_b32 m0, s78
	s_add_u32 s38, s6, 0x80080
	global_load_lds_dwordx4 v[0:1], off
	v_lshl_add_u64 v[0:1], v[2:3], 0, s[36:37]
	s_mov_b32 m0, s79
	s_addc_u32 s39, s7, 0
	global_load_lds_dwordx4 v[0:1], off
	s_add_i32 m0, s70, 0x1c000
	v_lshl_add_u64 v[0:1], s[38:39], 0, v[144:145]
	global_load_lds_dwordx4 v[0:1], off
	v_lshl_add_u64 v[0:1], s[38:39], 0, v[146:147]
	s_add_i32 m0, s70, 0x1e000
	s_cmpk_lt_u32 s2, 0x100
	global_load_lds_dwordx4 v[0:1], off
	v_lshlrev_b32_e32 v1, 2, v182
	v_lshl_or_b32 v0, v182, 6, v183
	v_and_b32_e32 v1, 32, v1
	v_bitop3_b32 v2, v0, s18, v1 bitop3:0xde
	v_lshlrev_b32_e32 v0, 2, v181
	v_mov_b32_e32 v1, v145
	v_lshl_add_u64 v[152:153], s[48:49], 0, v[0:1]
	v_lshlrev_b32_e32 v0, 9, v221
	v_and_b32_e32 v0, 0x70000, v0
	v_lshlrev_b32_e32 v1, 12, v187
	v_or3_b32 v0, v185, v0, v1
	v_add_u32_e32 v154, v0, v186
	v_lshlrev_b32_e32 v0, 5, v188
	v_and_b32_e32 v0, 0xf0000, v0
	s_waitcnt vmcnt(6)
	v_or3_b32 v0, v185, v0, v1
	v_lshl_or_b32 v193, s19, 7, v184
	s_cselect_b64 s[38:39], -1, 0
	v_add_u32_e32 v156, v0, v186
	s_add_i32 s82, 0, 0x10000
	s_add_i32 s83, 0, 0x14000
	v_mbcnt_lo_u32_b32 v0, -1, 0
	v_lshl_or_b32 v192, s3, 6, v182
	s_ashr_i32 s80, s34, 31
	s_mov_b32 s81, s34
	v_or_b32_e32 v194, s19, v181
	v_mov_b32_e32 v155, v145
	v_mov_b32_e32 v157, v145
	v_mov_b64_e32 v[158:159], 0x580
	v_mov_b64_e32 v[160:161], 0x57f
	v_add_u32_e32 v195, s82, v193
	v_add_u32_e32 v196, s83, v193
	v_add_u32_e32 v197, 0, v2
	v_mbcnt_hi_u32_b32 v198, -1, v0
	s_mov_b32 s40, 0x3a000000
	s_mov_b32 s84, 0x800000
	s_movk_i32 s88, 0x2c00
	s_mov_b32 s89, 0
	s_barrier
	v_mov_b32_e32 v217, 0x358637bd
	s_nop 0
	v_add_f32_e32 v200, v200, v201
	v_add_f32_e32 v202, v202, v203
	v_add_f32_e32 v204, v204, v205
	v_add_f32_e32 v206, v206, v207
	v_add_f32_e32 v208, v208, v209
	v_add_f32_e32 v210, v210, v211
	v_add_f32_e32 v212, v212, v213
	v_add_f32_e32 v214, v214, v215
	v_add_f32_e32 v200, v200, v202
	v_add_f32_e32 v204, v204, v206
	v_add_f32_e32 v208, v208, v210
	v_add_f32_e32 v212, v212, v214
	v_add_f32_e32 v200, v200, v204
	v_add_f32_e32 v208, v208, v212
	v_add_f32_e32 v200, v200, v208
	s_nop 1
	v_add_f32_dpp v204, v200, v200 quad_perm:[1,0,3,2] row_mask:0xf bank_mask:0xf
	v_fmamk_f32 v204, v204, 0x3a000000, v217
	v_rsq_f32_e32 v204, v204
	s_lshl_b32 s96, s95, 7
	s_add_i32 s96, s96, 0x21000
	v_lshrrev_b32_e32 v216, 1, v220
	v_lshl_add_u32 v216, v216, 2, s96
	ds_write_b32 v216, v204
	s_mov_b32 s99, 2
	s_branch .LBB0_258

; #define PG8_STAGE(bufoff, gbase, voff) do { _Pragma("unroll") for (int _i = 0; _i < 2; ++_i) \
;         __builtin_amdgcn_global_load_lds((const unsigned*)((const char*)(gbase) + (voff)[_i]), (LAS unsigned*)(lds + (bufoff) + ldsw + _i * 8192), 16, 0, 0); } while (0)
; #define PG8_WAIT_V(n) asm volatile("s_waitcnt vmcnt(" #n ")" ::: "memory")
; #define PG8_BAR __builtin_amdgcn_s_barrier()
; __device__ __forceinline__ void load_rstd(const float* part, int row0, int fq, float (&rs)[2][4]) {
; #pragma unroll
;     for (int ai = 0; ai < 2; ++ai)
; #pragma unroll
;         for (int m = 0; m < 4; ++m) { const float* p = part + (size_t)(row0 + ai * HALF + m * 16) * NPART + fq * 8;
;             const f32x4 a = *(const f32x4*)p, b = *(const f32x4*)(p + 4); float s = ((a[0] + a[1]) + (a[2] + a[3])) + ((b[0] + b[1]) + (b[2] + b[3]));
;             s += __shfl_xor(s, 16); s += __shfl_xor(s, 32); rs[ai][m] = rsqrtf(s * (1.0f / D) + RMS_EPS); }
; template <class Epi, class Sched, bool ALIGN_EPI>
; __device__ __forceinline__ void gemm_phase(LAS unsigned char* lds, const Gemm g, const Sched& S, const Epi& E) {
;     ...
;     PG8_STAGE(PG8_SB(0, 0), cB, voffB); PG8_STAGE(PG8_SB(0, 1), cB + hB, voffB); PG8_STAGE(PG8_SA(0, 0), cA, voffA); PG8_STAGE(PG8_SA(0, 1), cA + hA, voffA);
;     if (wr == 1) PG8_BAR;
;     PG8_WAIT_V(2); PG8_BAR;
;     PG8_STAGE(PG8_SB(1, 0), cB + kstep, voffB); PG8_STAGE(PG8_SA(1, 0), cA + kstep, voffA); PG8_STAGE(PG8_SB(1, 1), cB + hB + kstep, voffB);
;     PG8_WAIT_V(6); PG8_BAR;
.LBB0_1142:
	s_lshl_b32 s18, s26, 5
	s_mov_b64 s[26:27], 0x80
	s_and_b32 s33, s18, 0x60
	s_add_i32 m0, s58, 0x18000
	v_lshl_add_u64 v[6:7], v[6:7], 0, s[26:27]
	s_lshl_b32 s22, s3, 13
	s_lshl_b32 s30, s33, 7
	s_waitcnt vmcnt(2)
	s_barrier
	v_lshrrev_b32_e32 v204, 1, v220
	s_lshl_b32 s96, s11, 8
	s_lshl_b32 s97, s95, 5
	s_add_i32 s96, s96, s97
	v_add_u32_e32 v204, s96, v204
	v_and_b32_e32 v205, 1, v220
	v_lshlrev_b32_e32 v205, 6, v205
	v_lshl_add_u32 v204, v204, 7, v205
	s_add_u32 s96, s14, 0xc300000
	s_addc_u32 s97, s15, 0
	global_load_dwordx4 v[188:191], v204, s[96:97]
	global_load_dwordx4 v[192:195], v204, s[96:97] offset:16
	global_load_dwordx4 v[196:199], v204, s[96:97] offset:32
	global_load_dwordx4 v[200:203], v204, s[96:97] offset:48
	global_load_lds_dwordx4 v[6:7], off
	v_lshl_add_u64 v[4:5], v[4:5], 0, s[26:27]
	s_add_i32 m0, s58, 0x1a000
	s_add_i32 s62, s58, 0x8000
	s_add_i32 s63, s58, 0xa000
	global_load_lds_dwordx4 v[4:5], off
	v_lshl_add_u64 v[0:1], v[0:1], 0, s[26:27]
	s_mov_b32 m0, s62
	s_add_u32 s18, s6, 0x80080
	global_load_lds_dwordx4 v[0:1], off
	v_lshl_add_u64 v[0:1], v[2:3], 0, s[26:27]
	s_mov_b32 m0, s63
	s_addc_u32 s19, s7, 0
	global_load_lds_dwordx4 v[0:1], off
	s_add_i32 m0, s58, 0x1c000
	v_lshl_add_u64 v[0:1], s[18:19], 0, v[148:149]
	global_load_lds_dwordx4 v[0:1], off
	v_lshl_add_u64 v[0:1], s[18:19], 0, v[144:145]
	s_add_i32 m0, s58, 0x1e000
	v_and_b32_e32 v2, 32, v180
	global_load_lds_dwordx4 v[0:1], off
	v_and_b32_e32 v0, 15, v221
	v_lshlrev_b32_e32 v1, 1, v11
	v_lshl_or_b32 v181, s3, 6, v0
	v_lshl_or_b32 v0, v0, 6, v1
	v_bitop3_b32 v3, v0, s22, v2 bitop3:0xde
	v_lshlrev_b32_e32 v0, 6, v221
	s_movk_i32 s3, 0x3c0
	v_and_or_b32 v0, v0, s3, v1
	v_bitop3_b32 v182, s30, v0, v2 bitop3:0xf6
	v_lshlrev_b32_e32 v0, 2, v11
	v_mov_b32_e32 v1, v149
	v_lshl_add_u64 v[152:153], s[48:49], 0, v[0:1]
	v_lshlrev_b32_e32 v0, 9, v221
	v_and_b32_e32 v0, 0x70000, v0
	v_lshlrev_b32_e32 v1, 12, v12
	v_or3_b32 v0, v9, v0, v1
	v_add_u32_e32 v154, v0, v10
	v_lshlrev_b32_e32 v0, 5, v8
	v_and_b32_e32 v0, 0xf0000, v0
	s_waitcnt vmcnt(6)
	s_cmpk_lt_u32 s2, 0x100
	v_or3_b32 v0, v9, v0, v1
	s_cselect_b64 s[30:31], -1, 0
	v_add_u32_e32 v156, v0, v10
	s_add_i32 s66, 0, 0x10000
	s_add_i32 s67, 0, 0x14000
	v_mbcnt_lo_u32_b32 v0, -1, 0
	s_ashr_i32 s64, s34, 31
	s_mov_b32 s65, s34
	v_or_b32_e32 v183, s33, v11
	v_mov_b32_e32 v155, v149
	v_mov_b32_e32 v157, v149
	v_mov_b64_e32 v[158:159], 0x580
	v_mov_b64_e32 v[160:161], 0x57f
	v_add_u32_e32 v184, s66, v182
	v_add_u32_e32 v185, s67, v182
	v_add_u32_e32 v186, 0, v3
	v_mbcnt_hi_u32_b32 v187, -1, v0
	s_mov_b32 s36, 0x3a000000
	s_mov_b32 s38, 0x358637bd
	s_mov_b32 s68, 0x800000
	s_movk_i32 s69, 0x2c00
	s_mov_b32 s70, 0
	s_barrier
	v_mov_b32_e32 v205, 0x358637bd
	s_nop 0
	v_add_f32_e32 v188, v188, v189
	v_add_f32_e32 v190, v190, v191
	v_add_f32_e32 v192, v192, v193
	v_add_f32_e32 v194, v194, v195
	v_add_f32_e32 v196, v196, v197
	v_add_f32_e32 v198, v198, v199
	v_add_f32_e32 v200, v200, v201
	v_add_f32_e32 v202, v202, v203
	v_add_f32_e32 v188, v188, v190
	v_add_f32_e32 v192, v192, v194
	v_add_f32_e32 v196, v196, v198
	v_add_f32_e32 v200, v200, v202
	v_add_f32_e32 v188, v188, v192
	v_add_f32_e32 v196, v196, v200
	v_add_f32_e32 v188, v188, v196
	s_nop 1
	v_add_f32_dpp v192, v188, v188 quad_perm:[1,0,3,2] row_mask:0xf bank_mask:0xf
	v_fmamk_f32 v192, v192, 0x3a000000, v205
	v_rsq_f32_e32 v192, v192
	s_lshl_b32 s96, s95, 7
	s_add_i32 s96, s96, 0x21000
	v_lshrrev_b32_e32 v204, 1, v220
	v_lshl_add_u32 v204, v204, 2, s96
	ds_write_b32 v204, v192
	s_mov_b32 s99, 2
	s_branch .LBB0_1145
